# final RMSNorm: nt hint on write-once f32 output stores, gain loads cached normally, read-once prep loads nt
# baseline (speedup 1.0000x reference)
; __device__ __forceinline__ f32x2 unpk_f16(unsigned u) { const h16x2_t h = __builtin_bit_cast(h16x2_t, u); return __builtin_convertvector(h, f32x2); }
; __device__ __forceinline__ float rstd_of(u64 ssq) { return frsq((float)ssq * (1.0f / (2048.0f * 16777216.0f)) + EPS); }
; __global__ void __launch_bounds__(NTHREADS, 2) fwd_kernel(Args a) {
;     ...
;             for (int r = gw; r < T; r += nw) {
;                 const float rs = rstd_of(ssq[r]); const bf16_t* hr = (const bf16_t*)(ws + WS_H16) + (size_t)r * D; float* orow = out + (size_t)r * D;
; #pragma unroll
;                 for (int i = 0; i < 8; ++i) { const int cidx = (i * 64 + lane) * 4; const u32x2 hw = *(const u32x2*)(hr + cidx); const f32x4 gg = *(const f32x4*)(fg + cidx);
;                     const f32x2 a2 = unpk_f16(hw.x), b2 = unpk_f16(hw.y); f32x4 v; v[0] = a2.x; v[1] = a2.y; v[2] = b2.x; v[3] = b2.y; *(f32x4*)(orow + cidx) = v * rs * gg; }
;             }
.LBB0_964:
	global_load_dwordx2 v[22:23], v[10:11], off nt
	global_load_dwordx2 v[24:25], v[14:15], off offset:-2048 nt
	global_load_dwordx4 v[18:21], v[0:1], off
	global_load_dwordx2 v[58:59], v[14:15], off offset:-1536 nt
	global_load_dwordx4 v[60:63], v[0:1], off offset:1024
	global_load_dwordx2 v[64:65], v[14:15], off offset:-1024 nt
	global_load_dwordx4 v[66:69], v[0:1], off offset:2048
	global_load_dwordx2 v[70:71], v[14:15], off offset:-512 nt
	global_load_dwordx4 v[72:75], v[0:1], off offset:3072
	global_load_dwordx2 v[76:77], v[14:15], off nt
	global_load_dwordx4 v[78:81], v[2:3], off
	global_load_dwordx2 v[82:83], v[14:15], off offset:512 nt
	global_load_dwordx4 v[84:87], v[4:5], off
	global_load_dwordx2 v[88:89], v[14:15], off offset:1024 nt
	global_load_dwordx4 v[90:93], v[6:7], off
	global_load_dwordx2 v[94:95], v[14:15], off offset:1536 nt
	global_load_dwordx4 v[96:99], v[8:9], off
	s_movk_i32 s2, 0xf000
	v_add_co_u32_e32 v26, vcc, s2, v12
	v_add_u32_e32 v16, s6, v16
	s_nop 0
	v_addc_co_u32_e32 v27, vcc, -1, v13, vcc
	v_cmp_lt_i32_e32 vcc, s36, v16
	v_lshl_add_u64 v[10:11], v[10:11], 0, s[8:9]
	s_or_b64 s[14:15], vcc, s[14:15]
	s_waitcnt vmcnt(16)
	v_ffbh_u32_e32 v17, v23
	v_min_u32_e32 v17, 32, v17
	v_lshlrev_b64 v[22:23], v17, v[22:23]
	v_min_u32_e32 v22, 1, v22
	v_or_b32_e32 v22, v23, v22
	v_cvt_f32_u32_e32 v22, v22
	v_sub_u32_e32 v17, 32, v17
	s_waitcnt vmcnt(15)
	v_cvt_f32_f16_sdwa v29, v24 dst_sel:DWORD dst_unused:UNUSED_PAD src0_sel:WORD_1
	v_cvt_f32_f16_e32 v28, v24
	v_ldexp_f32 v17, v22, v17
	v_fmamk_f32 v17, v17, 0x2e000000, v239
	v_cvt_f32_f16_sdwa v31, v25 dst_sel:DWORD dst_unused:UNUSED_PAD src0_sel:WORD_1
	v_cvt_f32_f16_e32 v30, v25
	v_rsq_f32_e32 v22, v17
	s_nop 0
	v_pk_mul_f32 v[24:25], v[22:23], v[28:29] op_sel_hi:[0,1]
	v_pk_mul_f32 v[28:29], v[22:23], v[30:31] op_sel_hi:[0,1]
	s_waitcnt vmcnt(14)
	v_pk_mul_f32 v[20:21], v[20:21], v[28:29]
	v_pk_mul_f32 v[18:19], v[18:19], v[24:25]
	global_store_dwordx4 v[26:27], v[18:21], off offset:-3072 nt
	s_waitcnt vmcnt(14)
	s_nop 1
	v_mov_b64_e32 v[24:25], v[58:59]
	s_nop 0
	s_waitcnt vmcnt(13)
	s_nop 1
	v_mov_b64_e32 v[18:19], v[60:61]
	v_mov_b64_e32 v[20:21], v[62:63]
	v_cvt_f32_f16_sdwa v29, v24 dst_sel:DWORD dst_unused:UNUSED_PAD src0_sel:WORD_1
	v_cvt_f32_f16_e32 v28, v24
	v_cvt_f32_f16_sdwa v31, v25 dst_sel:DWORD dst_unused:UNUSED_PAD src0_sel:WORD_1
	v_cvt_f32_f16_e32 v30, v25
	v_pk_mul_f32 v[24:25], v[22:23], v[28:29] op_sel_hi:[0,1]
	v_pk_mul_f32 v[18:19], v[18:19], v[24:25]
	v_pk_mul_f32 v[28:29], v[22:23], v[30:31] op_sel_hi:[0,1]
	v_pk_mul_f32 v[20:21], v[20:21], v[28:29]
	global_store_dwordx4 v[26:27], v[18:21], off offset:-2048 nt
	s_waitcnt vmcnt(13)
	s_nop 1
	v_mov_b64_e32 v[24:25], v[64:65]
	s_nop 0
	s_waitcnt vmcnt(12)
	s_nop 1
	v_mov_b64_e32 v[18:19], v[66:67]
	v_mov_b64_e32 v[20:21], v[68:69]
	v_cvt_f32_f16_sdwa v29, v24 dst_sel:DWORD dst_unused:UNUSED_PAD src0_sel:WORD_1
	v_cvt_f32_f16_e32 v28, v24
	v_cvt_f32_f16_sdwa v31, v25 dst_sel:DWORD dst_unused:UNUSED_PAD src0_sel:WORD_1
	v_cvt_f32_f16_e32 v30, v25
	v_pk_mul_f32 v[24:25], v[22:23], v[28:29] op_sel_hi:[0,1]
	v_pk_mul_f32 v[18:19], v[18:19], v[24:25]
	v_pk_mul_f32 v[28:29], v[22:23], v[30:31] op_sel_hi:[0,1]
	v_pk_mul_f32 v[20:21], v[20:21], v[28:29]
	global_store_dwordx4 v[26:27], v[18:21], off offset:-1024 nt
	s_waitcnt vmcnt(12)
	s_nop 1
	v_mov_b64_e32 v[24:25], v[70:71]
	s_nop 0
	s_waitcnt vmcnt(11)
	s_nop 1
	v_mov_b64_e32 v[18:19], v[72:73]
	v_mov_b64_e32 v[20:21], v[74:75]
	v_cvt_f32_f16_sdwa v27, v24 dst_sel:DWORD dst_unused:UNUSED_PAD src0_sel:WORD_1
	v_cvt_f32_f16_e32 v26, v24
	v_cvt_f32_f16_sdwa v29, v25 dst_sel:DWORD dst_unused:UNUSED_PAD src0_sel:WORD_1
	v_cvt_f32_f16_e32 v28, v25
	v_pk_mul_f32 v[24:25], v[22:23], v[26:27] op_sel_hi:[0,1]
	v_pk_mul_f32 v[18:19], v[18:19], v[24:25]
	v_pk_mul_f32 v[26:27], v[22:23], v[28:29] op_sel_hi:[0,1]
	v_pk_mul_f32 v[20:21], v[20:21], v[26:27]
	global_store_dwordx4 v[12:13], v[18:21], off offset:-4096 nt
	s_waitcnt vmcnt(11)
	s_nop 1
	v_mov_b64_e32 v[24:25], v[76:77]
	s_nop 0
	s_waitcnt vmcnt(10)
	s_nop 1
	v_mov_b64_e32 v[18:19], v[78:79]
	v_mov_b64_e32 v[20:21], v[80:81]
	v_cvt_f32_f16_sdwa v27, v24 dst_sel:DWORD dst_unused:UNUSED_PAD src0_sel:WORD_1
	v_cvt_f32_f16_e32 v26, v24
	v_cvt_f32_f16_sdwa v29, v25 dst_sel:DWORD dst_unused:UNUSED_PAD src0_sel:WORD_1
	v_cvt_f32_f16_e32 v28, v25
	v_pk_mul_f32 v[24:25], v[22:23], v[26:27] op_sel_hi:[0,1]
	v_pk_mul_f32 v[18:19], v[18:19], v[24:25]
	v_pk_mul_f32 v[26:27], v[22:23], v[28:29] op_sel_hi:[0,1]
	v_pk_mul_f32 v[20:21], v[20:21], v[26:27]
	global_store_dwordx4 v[12:13], v[18:21], off offset:-3072 nt
	s_waitcnt vmcnt(10)
	s_nop 1
	v_mov_b64_e32 v[24:25], v[82:83]
	s_nop 0
	s_waitcnt vmcnt(9)
	s_nop 1
	v_mov_b64_e32 v[18:19], v[84:85]
	v_mov_b64_e32 v[20:21], v[86:87]
	v_cvt_f32_f16_sdwa v27, v24 dst_sel:DWORD dst_unused:UNUSED_PAD src0_sel:WORD_1
	v_cvt_f32_f16_e32 v26, v24
	v_cvt_f32_f16_sdwa v29, v25 dst_sel:DWORD dst_unused:UNUSED_PAD src0_sel:WORD_1
	v_cvt_f32_f16_e32 v28, v25
	v_pk_mul_f32 v[24:25], v[22:23], v[26:27] op_sel_hi:[0,1]
	v_pk_mul_f32 v[18:19], v[18:19], v[24:25]
	v_pk_mul_f32 v[26:27], v[22:23], v[28:29] op_sel_hi:[0,1]
	v_pk_mul_f32 v[20:21], v[20:21], v[26:27]
	global_store_dwordx4 v[12:13], v[18:21], off offset:-2048 nt
	s_waitcnt vmcnt(9)
	s_nop 1
	v_mov_b64_e32 v[24:25], v[88:89]
	s_nop 0
	s_waitcnt vmcnt(8)
	s_nop 1
	v_mov_b64_e32 v[18:19], v[90:91]
	v_mov_b64_e32 v[20:21], v[92:93]
	v_cvt_f32_f16_sdwa v27, v24 dst_sel:DWORD dst_unused:UNUSED_PAD src0_sel:WORD_1
	v_cvt_f32_f16_e32 v26, v24
	v_cvt_f32_f16_sdwa v29, v25 dst_sel:DWORD dst_unused:UNUSED_PAD src0_sel:WORD_1
	v_cvt_f32_f16_e32 v28, v25
	v_pk_mul_f32 v[24:25], v[22:23], v[26:27] op_sel_hi:[0,1]
	v_pk_mul_f32 v[18:19], v[18:19], v[24:25]
	v_pk_mul_f32 v[26:27], v[22:23], v[28:29] op_sel_hi:[0,1]
	v_pk_mul_f32 v[20:21], v[20:21], v[26:27]
	global_store_dwordx4 v[12:13], v[18:21], off offset:-1024 nt
	s_waitcnt vmcnt(8)
	s_nop 1
	v_mov_b64_e32 v[24:25], v[94:95]
	s_nop 0
	s_waitcnt vmcnt(7)
	s_nop 1
	v_mov_b64_e32 v[18:19], v[96:97]
	v_mov_b64_e32 v[20:21], v[98:99]
	v_lshl_add_u64 v[14:15], v[14:15], 0, s[12:13]
	v_cvt_f32_f16_sdwa v27, v24 dst_sel:DWORD dst_unused:UNUSED_PAD src0_sel:WORD_1
	v_cvt_f32_f16_e32 v26, v24
	v_cvt_f32_f16_sdwa v29, v25 dst_sel:DWORD dst_unused:UNUSED_PAD src0_sel:WORD_1
	v_cvt_f32_f16_e32 v28, v25
	v_pk_mul_f32 v[24:25], v[22:23], v[26:27] op_sel_hi:[0,1]
	v_pk_mul_f32 v[18:19], v[18:19], v[24:25]
	v_pk_mul_f32 v[22:23], v[22:23], v[28:29] op_sel_hi:[0,1]
	v_pk_mul_f32 v[20:21], v[20:21], v[22:23]
	global_store_dwordx4 v[12:13], v[18:21], off nt
	v_lshl_add_u64 v[12:13], v[12:13], 0, s[10:11]
	s_andn2_b64 exec, exec, s[14:15]
	s_cbranch_execnz .LBB0_964
